# FFN2 walks K from the last k-block down: the hidden columns FFN1 wrote last (still in L2) are consumed first
# speedup vs baseline: 1.0043x; 1.0018x over previous
; DI int TID() { int t = (int)__builtin_amdgcn_workitem_id_x(); asm volatile("" : "+v"(t)); return t; }
; #define BLOAD(A_, B_, kt) do { _Pragma("unroll") for (int i = 0; i < 4; ++i) { \
;     A_[i] = *(const u32x4*)((const char*)Ap + (aoff + (unsigned)(32 * i * lda + (kt) * 64) * 2u)); B_[i] = *(const u32x4*)((const char*)Wt + (woff + (unsigned)(32 * i * K + (kt) * 64) * 2u)); } } while (0)
; #define BLOAD(A_, B_, kt) do { _Pragma("unroll") for (int i = 0; i < 4; ++i) { \
;     A_[i] = *(const u32x4*)((const char*)Ap + (aoff + (unsigned)(32 * i * lda + (kt) * 64) * 2u)); B_[i] = *(const u32x4*)((const char*)Wt + (woff + (unsigned)(32 * i * K + (kt) * 64) * 2u)); } } while (0)
; #define BSTORE(A_, B_, buf) do { _Pragma("unroll") for (int i = 0; i < 4; ++i) { \
;     *(u32x4*)&As[(buf) * GBUF + (srow + 32 * i) * LDT + sc8] = A_[i]; \
;     *(u32x4*)&Bs[(buf) * GBUF + (srow + 32 * i) * LDT + sc8] = B_[i]; } } while (0)
; template <int NK>
; DI void gemm_run(PF& pf, const u16* __restrict__ Ap, int lda, const u16* __restrict__ Wt, f32x16 (&acc)[2][2], char* smem) {
;     ...
;   __builtin_amdgcn_s_setprio(0);
;   __syncthreads();
;   BSTORE(pf.a0, pf.b0, 0);
;   BLOAD(pf.a0, pf.b0, 2);
;   __syncthreads();
; DI void tile_ffn2(const Params& p, int l, const Chunk& ck, int tile, int next, PF& pf, char* smem) {
;   float* Cs = (float*)smem;
;   const int tid = TID(); const int mi = tile & (MTN - 1), ni = tile >> MTS; const int m0 = mi * 128, n0 = ni * 128;
;   f32x16 acc[2][2]; zero_acc(acc);
;   { const u16* Ap; const u16* Wt; ffn2_ptrs(p, l, tile, Ap, Wt); gemm_run<64>(pf, Ap, 4096, Wt, acc, smem); }
.LBB1_206:
	s_add_i32 s25, s26, s78
	s_cmpk_gt_i32 s25, 0x1ff
	s_cselect_b64 s[28:29], -1, 0
	s_cmpk_lt_i32 s25, 0x200
	s_cselect_b32 s0, s25, -1
	s_and_b32 s16, s41, 0x3f80000
	s_and_b32 s36, s26, 0xffffff80
	s_add_i32 s26, s26, s36
	s_lshl_b32 s36, s36, 1
	s_lshl_b32 s16, s16, 1
	s_add_u32 vcc_lo, s17, s16
	v_mov_b32_e32 v0, v172
	s_addc_u32 vcc_hi, s27, 0
	s_ashr_i32 s37, s36, 31
	s_lshl_b64 s[30:31], s[36:37], 6
	s_add_u32 s30, s34, s30
	s_addc_u32 s31, s40, s31
	s_setprio 0
	s_waitcnt lgkmcnt(0)
	s_lshr_b32 s16, s16, 7
	s_add_u32 s42, s17, s16
	s_addc_u32 s43, s27, 0
	s_add_u32 s42, s42, 0x7f00000
	s_addc_u32 s43, s43, 0
	s_add_u32 s30, s30, 0x7f0000
	s_addc_u32 s31, s31, 0
	v_and_b32_e32 v174, 63, v172
	v_lshrrev_b32_e32 v175, 6, v172
	v_bfe_u32 v176, v174, 4, 2
	v_lshrrev_b32_e32 v177, 1, v176
	v_xor_b32_e32 v176, v176, v177
	v_and_b32_e32 v176, 1, v176
	v_lshl_or_b32 v176, v176, 1, v177
	v_xor_b32_e32 v176, v176, v174
	v_and_b32_e32 v176, 3, v176
	v_lshlrev_b32_e32 v176, 4, v176
	v_lshrrev_b32_e32 v177, 2, v174
	v_lshl_add_u32 v137, v175, 5, v177
	v_lshl_add_u32 v137, v137, 6, v176
	v_mov_b32_e32 v150, v137
	v_lshl_add_u32 v151, v175, 6, v177
	v_lshl_add_u32 v151, v151, 6, v176
	v_mov_b32_e32 v152, v151
	v_mov_b32_e32 v153, v151
	v_mov_b32_e32 v154, v151
	v_readfirstlane_b32 s16, v175
	s_lshl_b32 s0, s16, 12
	s_lshl_b32 s16, s16, 11
	s_add_u32 s0, s0, 0x2000
	v_bfe_u32 v176, v174, 2, 2
	v_lshrrev_b32_e32 v177, 1, v176
	v_xor_b32_e32 v176, v176, v177
	v_and_b32_e32 v176, 1, v176
	v_lshl_or_b32 v176, v176, 1, v177
	v_lshrrev_b32_e32 v177, 4, v174
	v_xor_b32_e32 v176, v176, v177
	v_lshlrev_b32_e32 v176, 4, v176
	v_and_b32_e32 v174, 15, v174
	v_lshl_add_u32 v174, v174, 6, v176
	v_lshrrev_b32_e32 v176, 1, v175
	v_and_b32_e32 v177, 1, v175
	v_lshl_add_u32 v126, v176, 12, v174
	v_lshl_add_u32 v128, v177, 12, v174
	v_add_u32_e32 v128, 0x2000, v128
	s_barrier
	v_mov_b32_e32 v2, 0
	v_mov_b32_e32 v3, 0
	v_mov_b32_e32 v4, 0
	v_mov_b32_e32 v5, 0
	v_mov_b32_e32 v6, 0
	v_mov_b32_e32 v7, 0
	v_mov_b32_e32 v8, 0
	v_mov_b32_e32 v9, 0
	v_mov_b32_e32 v10, 0
	v_mov_b32_e32 v11, 0
	v_mov_b32_e32 v12, 0
	v_mov_b32_e32 v13, 0
	v_mov_b32_e32 v14, 0
	v_mov_b32_e32 v15, 0
	v_mov_b32_e32 v16, 0
	v_mov_b32_e32 v17, 0
	v_mov_b32_e32 v18, 0
	v_mov_b32_e32 v19, 0
	v_mov_b32_e32 v20, 0
	v_mov_b32_e32 v21, 0
	v_mov_b32_e32 v22, 0
	v_mov_b32_e32 v23, 0
	v_mov_b32_e32 v24, 0
	v_mov_b32_e32 v25, 0
	v_mov_b32_e32 v26, 0
	v_mov_b32_e32 v27, 0
	v_mov_b32_e32 v28, 0
	v_mov_b32_e32 v29, 0
	v_mov_b32_e32 v30, 0
	v_mov_b32_e32 v31, 0
	v_mov_b32_e32 v32, 0
	v_mov_b32_e32 v33, 0
	v_mov_b32_e32 v34, 0
	v_mov_b32_e32 v35, 0
	v_mov_b32_e32 v36, 0
	v_mov_b32_e32 v37, 0
	v_mov_b32_e32 v38, 0
	v_mov_b32_e32 v39, 0
	v_mov_b32_e32 v40, 0
	v_mov_b32_e32 v41, 0
	v_mov_b32_e32 v42, 0
	v_mov_b32_e32 v43, 0
	v_mov_b32_e32 v44, 0
	v_mov_b32_e32 v45, 0
	v_mov_b32_e32 v46, 0
	v_mov_b32_e32 v47, 0
	v_mov_b32_e32 v48, 0
	v_mov_b32_e32 v49, 0
	v_mov_b32_e32 v50, 0
	v_mov_b32_e32 v51, 0
	v_mov_b32_e32 v52, 0
	v_mov_b32_e32 v53, 0
	v_mov_b32_e32 v54, 0
	v_mov_b32_e32 v55, 0
	v_mov_b32_e32 v56, 0
	v_mov_b32_e32 v57, 0
	v_mov_b32_e32 v58, 0
	v_mov_b32_e32 v59, 0
	v_mov_b32_e32 v60, 0
	v_mov_b32_e32 v61, 0
	v_mov_b32_e32 v62, 0
	v_mov_b32_e32 v63, 0
	v_mov_b32_e32 v64, 0
	v_mov_b32_e32 v65, 0
	v_mov_b32_e32 v74, 0
	v_mov_b32_e32 v75, 0
	v_mov_b32_e32 v76, 0
	v_mov_b32_e32 v77, 0
	v_mov_b32_e32 v78, 0
	v_mov_b32_e32 v79, 0
	v_mov_b32_e32 v80, 0
	v_mov_b32_e32 v81, 0
	v_mov_b32_e32 v82, 0
	v_mov_b32_e32 v83, 0
	v_mov_b32_e32 v84, 0
	v_mov_b32_e32 v85, 0
	v_mov_b32_e32 v86, 0
	v_mov_b32_e32 v87, 0
	v_mov_b32_e32 v88, 0
	v_mov_b32_e32 v89, 0
	v_mov_b32_e32 v90, 0
	v_mov_b32_e32 v91, 0
	v_mov_b32_e32 v92, 0
	v_mov_b32_e32 v93, 0
	v_mov_b32_e32 v94, 0
	v_mov_b32_e32 v95, 0
	v_mov_b32_e32 v96, 0
	v_mov_b32_e32 v97, 0
	v_mov_b32_e32 v98, 0
	v_mov_b32_e32 v99, 0
	v_mov_b32_e32 v100, 0
	v_mov_b32_e32 v101, 0
	v_mov_b32_e32 v102, 0
	v_mov_b32_e32 v103, 0
	v_mov_b32_e32 v104, 0
	v_mov_b32_e32 v105, 0
	v_mov_b32_e32 v106, 0
	v_mov_b32_e32 v107, 0
	v_mov_b32_e32 v108, 0
	v_mov_b32_e32 v109, 0
	v_mov_b32_e32 v110, 0
	v_mov_b32_e32 v111, 0
	v_mov_b32_e32 v112, 0
	v_mov_b32_e32 v113, 0
	v_mov_b32_e32 v114, 0
	v_mov_b32_e32 v115, 0
	v_mov_b32_e32 v116, 0
	v_mov_b32_e32 v117, 0
	v_mov_b32_e32 v118, 0
	v_mov_b32_e32 v119, 0
	v_mov_b32_e32 v120, 0
	v_mov_b32_e32 v121, 0
	v_mov_b32_e32 v208, 0
	v_mov_b32_e32 v209, 0
	v_mov_b32_e32 v210, 0
	v_mov_b32_e32 v211, 0
	v_mov_b32_e32 v212, 0
	v_mov_b32_e32 v213, 0
	v_mov_b32_e32 v214, 0
	v_mov_b32_e32 v215, 0
	v_mov_b32_e32 v216, 0
	v_mov_b32_e32 v217, 0
	v_mov_b32_e32 v218, 0
	v_mov_b32_e32 v219, 0
	v_mov_b32_e32 v220, 0
	v_mov_b32_e32 v221, 0
	v_mov_b32_e32 v222, 0
	v_mov_b32_e32 v223, 0
	s_add_u32 m0, s16, 0x0
	s_nop 0
	global_load_lds_dwordx4 v137, s[42:43]
	global_load_lds_dwordx4 v150, s[42:43] offset:1024
	s_add_u32 m0, s0, 0x0
	s_nop 0
	global_load_lds_dwordx4 v151, s[30:31]
	global_load_lds_dwordx4 v152, s[30:31] offset:1024
	global_load_lds_dwordx4 v153, s[30:31] offset:2048
	global_load_lds_dwordx4 v154, s[30:31] offset:3072
	s_add_u32 m0, s16, 0x6000
	s_sub_u32 s42, s42, 0x100000
	s_subb_u32 s43, s43, 0
	global_load_lds_dwordx4 v137, s[42:43]
	global_load_lds_dwordx4 v150, s[42:43] offset:1024
	s_add_u32 m0, s0, 0x6000
	s_sub_u32 s30, s30, 0x10000
	s_subb_u32 s31, s31, 0
	global_load_lds_dwordx4 v151, s[30:31]
	global_load_lds_dwordx4 v152, s[30:31] offset:1024
	global_load_lds_dwordx4 v153, s[30:31] offset:2048
	global_load_lds_dwordx4 v154, s[30:31] offset:3072
	s_mov_b32 s46, 42
; #define BLOAD(A_, B_, kt) do { _Pragma("unroll") for (int i = 0; i < 4; ++i) { \
;     A_[i] = *(const u32x4*)((const char*)Ap + (aoff + (unsigned)(32 * i * lda + (kt) * 64) * 2u)); B_[i] = *(const u32x4*)((const char*)Wt + (woff + (unsigned)(32 * i * K + (kt) * 64) * 2u)); } } while (0)
; #define BLOAD(A_, B_, kt) do { _Pragma("unroll") for (int i = 0; i < 4; ++i) { \
;     A_[i] = *(const u32x4*)((const char*)Ap + (aoff + (unsigned)(32 * i * lda + (kt) * 64) * 2u)); B_[i] = *(const u32x4*)((const char*)Wt + (woff + (unsigned)(32 * i * K + (kt) * 64) * 2u)); } } while (0)
; #define BSTORE(A_, B_, buf) do { _Pragma("unroll") for (int i = 0; i < 4; ++i) { \
;     *(u32x4*)&As[(buf) * GBUF + (srow + 32 * i) * LDT + sc8] = A_[i]; \
;     *(u32x4*)&Bs[(buf) * GBUF + (srow + 32 * i) * LDT + sc8] = B_[i]; } } while (0)
; template <int NK>
; DI void gemm_run(PF& pf, const u16* __restrict__ Ap, int lda, const u16* __restrict__ Wt, f32x16 (&acc)[2][2], char* smem) {
;     ...
; #pragma unroll
;   for (int kt = 0; kt < nk; kt += 2) {
;     BCOMP(0);
;     BSTORE(pf.a1, pf.b1, 1);
;     if (kt + 3 < nk) BLOAD(pf.a1, pf.b1, kt + 3);
;     __syncthreads();
;     BCOMP(1);
;     if (kt + 2 < nk) { BSTORE(pf.a0, pf.b0, 0); if (kt + 4 < nk) BLOAD(pf.a0, pf.b0, kt + 4); }
;     __syncthreads();
;   }
.Lffn2_kloop:
	s_waitcnt vmcnt(6)
	s_barrier
	ds_read_b128 v[224:227], v126 offset:0
	ds_read_b128 v[240:243], v128 offset:0
	ds_read_b128 v[244:247], v128 offset:1024
	ds_read_b128 v[248:251], v128 offset:2048
	ds_read_b128 v[156:159], v128 offset:3072
	s_add_u32 m0, s16, 0xc000
	s_sub_u32 s42, s42, 0x100000
	s_subb_u32 s43, s43, 0
	global_load_lds_dwordx4 v137, s[42:43]
	global_load_lds_dwordx4 v150, s[42:43] offset:1024
	s_add_u32 m0, s0, 0xc000
	s_sub_u32 s30, s30, 0x10000
	s_subb_u32 s31, s31, 0
	global_load_lds_dwordx4 v151, s[30:31]
	global_load_lds_dwordx4 v152, s[30:31] offset:1024
	global_load_lds_dwordx4 v153, s[30:31] offset:2048
	global_load_lds_dwordx4 v154, s[30:31] offset:3072
	ds_read_b128 v[228:231], v126 offset:1024
	ds_read_b128 v[232:235], v126 offset:2048
	ds_read_b128 v[236:239], v126 offset:3072
	ds_read_b128 v[160:163], v128 offset:8192
	ds_read_b128 v[164:167], v128 offset:9216
	ds_read_b128 v[168:171], v128 offset:10240
	ds_read_b128 v[122:125], v128 offset:11264
	s_waitcnt lgkmcnt(10)
	v_mfma_f32_16x16x32_bf16 v[2:5], v[240:243], v[224:227], v[2:5]
	s_waitcnt lgkmcnt(9)
	v_mfma_f32_16x16x32_bf16 v[6:9], v[244:247], v[224:227], v[6:9]
	s_waitcnt lgkmcnt(8)
	v_mfma_f32_16x16x32_bf16 v[10:13], v[248:251], v[224:227], v[10:13]
	s_waitcnt lgkmcnt(7)
	v_mfma_f32_16x16x32_bf16 v[14:17], v[156:159], v[224:227], v[14:17]
	s_waitcnt lgkmcnt(6)
	v_mfma_f32_16x16x32_bf16 v[18:21], v[240:243], v[228:231], v[18:21]
	v_mfma_f32_16x16x32_bf16 v[22:25], v[244:247], v[228:231], v[22:25]
	v_mfma_f32_16x16x32_bf16 v[26:29], v[248:251], v[228:231], v[26:29]
	v_mfma_f32_16x16x32_bf16 v[30:33], v[156:159], v[228:231], v[30:33]
	s_waitcnt lgkmcnt(5)
	v_mfma_f32_16x16x32_bf16 v[34:37], v[240:243], v[232:235], v[34:37]
	v_mfma_f32_16x16x32_bf16 v[38:41], v[244:247], v[232:235], v[38:41]
	v_mfma_f32_16x16x32_bf16 v[42:45], v[248:251], v[232:235], v[42:45]
	v_mfma_f32_16x16x32_bf16 v[46:49], v[156:159], v[232:235], v[46:49]
	s_waitcnt lgkmcnt(4)
	v_mfma_f32_16x16x32_bf16 v[50:53], v[240:243], v[236:239], v[50:53]
	v_mfma_f32_16x16x32_bf16 v[54:57], v[244:247], v[236:239], v[54:57]
	v_mfma_f32_16x16x32_bf16 v[58:61], v[248:251], v[236:239], v[58:61]
	v_mfma_f32_16x16x32_bf16 v[62:65], v[156:159], v[236:239], v[62:65]
	s_waitcnt lgkmcnt(3)
	v_mfma_f32_16x16x32_bf16 v[74:77], v[160:163], v[224:227], v[74:77]
	s_waitcnt lgkmcnt(2)
	v_mfma_f32_16x16x32_bf16 v[78:81], v[164:167], v[224:227], v[78:81]
	s_waitcnt lgkmcnt(1)
	v_mfma_f32_16x16x32_bf16 v[82:85], v[168:171], v[224:227], v[82:85]
	s_waitcnt lgkmcnt(0)
	v_mfma_f32_16x16x32_bf16 v[86:89], v[122:125], v[224:227], v[86:89]
	v_mfma_f32_16x16x32_bf16 v[90:93], v[160:163], v[228:231], v[90:93]
	v_mfma_f32_16x16x32_bf16 v[94:97], v[164:167], v[228:231], v[94:97]
	v_mfma_f32_16x16x32_bf16 v[98:101], v[168:171], v[228:231], v[98:101]
	v_mfma_f32_16x16x32_bf16 v[102:105], v[122:125], v[228:231], v[102:105]
	v_mfma_f32_16x16x32_bf16 v[106:109], v[160:163], v[232:235], v[106:109]
	v_mfma_f32_16x16x32_bf16 v[110:113], v[164:167], v[232:235], v[110:113]
	v_mfma_f32_16x16x32_bf16 v[114:117], v[168:171], v[232:235], v[114:117]
	v_mfma_f32_16x16x32_bf16 v[118:121], v[122:125], v[232:235], v[118:121]
	v_mfma_f32_16x16x32_bf16 v[208:211], v[160:163], v[236:239], v[208:211]
	v_mfma_f32_16x16x32_bf16 v[212:215], v[164:167], v[236:239], v[212:215]
	v_mfma_f32_16x16x32_bf16 v[216:219], v[168:171], v[236:239], v[216:219]
	v_mfma_f32_16x16x32_bf16 v[220:223], v[122:125], v[236:239], v[220:223]
	s_waitcnt vmcnt(6)
	s_barrier
	ds_read_b128 v[224:227], v126 offset:24576
	ds_read_b128 v[240:243], v128 offset:24576
	ds_read_b128 v[244:247], v128 offset:25600
	ds_read_b128 v[248:251], v128 offset:26624
	ds_read_b128 v[156:159], v128 offset:27648
	s_add_u32 m0, s16, 0x0
	s_sub_u32 s42, s42, 0x100000
	s_subb_u32 s43, s43, 0
	global_load_lds_dwordx4 v137, s[42:43]
	global_load_lds_dwordx4 v150, s[42:43] offset:1024
	s_add_u32 m0, s0, 0x0
	s_sub_u32 s30, s30, 0x10000
	s_subb_u32 s31, s31, 0
	global_load_lds_dwordx4 v151, s[30:31]
	global_load_lds_dwordx4 v152, s[30:31] offset:1024
	global_load_lds_dwordx4 v153, s[30:31] offset:2048
	global_load_lds_dwordx4 v154, s[30:31] offset:3072
	ds_read_b128 v[228:231], v126 offset:25600
	ds_read_b128 v[232:235], v126 offset:26624
	ds_read_b128 v[236:239], v126 offset:27648
	ds_read_b128 v[160:163], v128 offset:32768
	ds_read_b128 v[164:167], v128 offset:33792
	ds_read_b128 v[168:171], v128 offset:34816
	ds_read_b128 v[122:125], v128 offset:35840
	s_waitcnt lgkmcnt(10)
	v_mfma_f32_16x16x32_bf16 v[2:5], v[240:243], v[224:227], v[2:5]
	s_waitcnt lgkmcnt(9)
	v_mfma_f32_16x16x32_bf16 v[6:9], v[244:247], v[224:227], v[6:9]
	s_waitcnt lgkmcnt(8)
	v_mfma_f32_16x16x32_bf16 v[10:13], v[248:251], v[224:227], v[10:13]
	s_waitcnt lgkmcnt(7)
	v_mfma_f32_16x16x32_bf16 v[14:17], v[156:159], v[224:227], v[14:17]
	s_waitcnt lgkmcnt(6)
	v_mfma_f32_16x16x32_bf16 v[18:21], v[240:243], v[228:231], v[18:21]
	v_mfma_f32_16x16x32_bf16 v[22:25], v[244:247], v[228:231], v[22:25]
	v_mfma_f32_16x16x32_bf16 v[26:29], v[248:251], v[228:231], v[26:29]
	v_mfma_f32_16x16x32_bf16 v[30:33], v[156:159], v[228:231], v[30:33]
	s_waitcnt lgkmcnt(5)
	v_mfma_f32_16x16x32_bf16 v[34:37], v[240:243], v[232:235], v[34:37]
	v_mfma_f32_16x16x32_bf16 v[38:41], v[244:247], v[232:235], v[38:41]
	v_mfma_f32_16x16x32_bf16 v[42:45], v[248:251], v[232:235], v[42:45]
	v_mfma_f32_16x16x32_bf16 v[46:49], v[156:159], v[232:235], v[46:49]
	s_waitcnt lgkmcnt(4)
	v_mfma_f32_16x16x32_bf16 v[50:53], v[240:243], v[236:239], v[50:53]
	v_mfma_f32_16x16x32_bf16 v[54:57], v[244:247], v[236:239], v[54:57]
	v_mfma_f32_16x16x32_bf16 v[58:61], v[248:251], v[236:239], v[58:61]
	v_mfma_f32_16x16x32_bf16 v[62:65], v[156:159], v[236:239], v[62:65]
	s_waitcnt lgkmcnt(3)
	v_mfma_f32_16x16x32_bf16 v[74:77], v[160:163], v[224:227], v[74:77]
	s_waitcnt lgkmcnt(2)
	v_mfma_f32_16x16x32_bf16 v[78:81], v[164:167], v[224:227], v[78:81]
	s_waitcnt lgkmcnt(1)
	v_mfma_f32_16x16x32_bf16 v[82:85], v[168:171], v[224:227], v[82:85]
	s_waitcnt lgkmcnt(0)
	v_mfma_f32_16x16x32_bf16 v[86:89], v[122:125], v[224:227], v[86:89]
	v_mfma_f32_16x16x32_bf16 v[90:93], v[160:163], v[228:231], v[90:93]
	v_mfma_f32_16x16x32_bf16 v[94:97], v[164:167], v[228:231], v[94:97]
	v_mfma_f32_16x16x32_bf16 v[98:101], v[168:171], v[228:231], v[98:101]
	v_mfma_f32_16x16x32_bf16 v[102:105], v[122:125], v[228:231], v[102:105]
	v_mfma_f32_16x16x32_bf16 v[106:109], v[160:163], v[232:235], v[106:109]
	v_mfma_f32_16x16x32_bf16 v[110:113], v[164:167], v[232:235], v[110:113]
	v_mfma_f32_16x16x32_bf16 v[114:117], v[168:171], v[232:235], v[114:117]
	v_mfma_f32_16x16x32_bf16 v[118:121], v[122:125], v[232:235], v[118:121]
	v_mfma_f32_16x16x32_bf16 v[208:211], v[160:163], v[236:239], v[208:211]
	v_mfma_f32_16x16x32_bf16 v[212:215], v[164:167], v[236:239], v[212:215]
	v_mfma_f32_16x16x32_bf16 v[216:219], v[168:171], v[236:239], v[216:219]
	v_mfma_f32_16x16x32_bf16 v[220:223], v[122:125], v[236:239], v[220:223]
	s_waitcnt vmcnt(6)
	s_barrier
; #define BLOAD(A_, B_, kt) do { _Pragma("unroll") for (int i = 0; i < 4; ++i) { \
;     A_[i] = *(const u32x4*)((const char*)Ap + (aoff + (unsigned)(32 * i * lda + (kt) * 64) * 2u)); B_[i] = *(const u32x4*)((const char*)Wt + (woff + (unsigned)(32 * i * K + (kt) * 64) * 2u)); } } while (0)
; #define BLOAD(A_, B_, kt) do { _Pragma("unroll") for (int i = 0; i < 4; ++i) { \
;     A_[i] = *(const u32x4*)((const char*)Ap + (aoff + (unsigned)(32 * i * lda + (kt) * 64) * 2u)); B_[i] = *(const u32x4*)((const char*)Wt + (woff + (unsigned)(32 * i * K + (kt) * 64) * 2u)); } } while (0)
; #define BSTORE(A_, B_, buf) do { _Pragma("unroll") for (int i = 0; i < 4; ++i) { \
;     *(u32x4*)&As[(buf) * GBUF + (srow + 32 * i) * LDT + sc8] = A_[i]; \
;     *(u32x4*)&Bs[(buf) * GBUF + (srow + 32 * i) * LDT + sc8] = B_[i]; } } while (0)
; template <int NK>
; DI void gemm_run(PF& pf, const u16* __restrict__ Ap, int lda, const u16* __restrict__ Wt, f32x16 (&acc)[2][2], char* smem) {
;     ...
; #pragma unroll
;   for (int kt = 0; kt < nk; kt += 2) {
;     BCOMP(0);
;     BSTORE(pf.a1, pf.b1, 1);
;     if (kt + 3 < nk) BLOAD(pf.a1, pf.b1, kt + 3);
;     __syncthreads();
;     BCOMP(1);
;     if (kt + 2 < nk) { BSTORE(pf.a0, pf.b0, 0); if (kt + 4 < nk) BLOAD(pf.a0, pf.b0, kt + 4); }
;     __syncthreads();
;   }
	ds_read_b128 v[224:227], v126 offset:49152
	ds_read_b128 v[240:243], v128 offset:49152
	ds_read_b128 v[244:247], v128 offset:50176
	ds_read_b128 v[248:251], v128 offset:51200
	ds_read_b128 v[156:159], v128 offset:52224
	s_add_u32 m0, s16, 0x6000
	s_sub_u32 s42, s42, 0x100000
	s_subb_u32 s43, s43, 0
	global_load_lds_dwordx4 v137, s[42:43]
	global_load_lds_dwordx4 v150, s[42:43] offset:1024
	s_add_u32 m0, s0, 0x6000
	s_sub_u32 s30, s30, 0x10000
	s_subb_u32 s31, s31, 0
	global_load_lds_dwordx4 v151, s[30:31]
	global_load_lds_dwordx4 v152, s[30:31] offset:1024
	global_load_lds_dwordx4 v153, s[30:31] offset:2048
	global_load_lds_dwordx4 v154, s[30:31] offset:3072
	ds_read_b128 v[228:231], v126 offset:50176
	ds_read_b128 v[232:235], v126 offset:51200
	ds_read_b128 v[236:239], v126 offset:52224
	ds_read_b128 v[160:163], v128 offset:57344
	ds_read_b128 v[164:167], v128 offset:58368
	ds_read_b128 v[168:171], v128 offset:59392
	ds_read_b128 v[122:125], v128 offset:60416
	s_waitcnt lgkmcnt(10)
	v_mfma_f32_16x16x32_bf16 v[2:5], v[240:243], v[224:227], v[2:5]
	s_waitcnt lgkmcnt(9)
	v_mfma_f32_16x16x32_bf16 v[6:9], v[244:247], v[224:227], v[6:9]
	s_waitcnt lgkmcnt(8)
	v_mfma_f32_16x16x32_bf16 v[10:13], v[248:251], v[224:227], v[10:13]
	s_waitcnt lgkmcnt(7)
	v_mfma_f32_16x16x32_bf16 v[14:17], v[156:159], v[224:227], v[14:17]
	s_waitcnt lgkmcnt(6)
	v_mfma_f32_16x16x32_bf16 v[18:21], v[240:243], v[228:231], v[18:21]
	v_mfma_f32_16x16x32_bf16 v[22:25], v[244:247], v[228:231], v[22:25]
	v_mfma_f32_16x16x32_bf16 v[26:29], v[248:251], v[228:231], v[26:29]
	v_mfma_f32_16x16x32_bf16 v[30:33], v[156:159], v[228:231], v[30:33]
	s_waitcnt lgkmcnt(5)
	v_mfma_f32_16x16x32_bf16 v[34:37], v[240:243], v[232:235], v[34:37]
	v_mfma_f32_16x16x32_bf16 v[38:41], v[244:247], v[232:235], v[38:41]
	v_mfma_f32_16x16x32_bf16 v[42:45], v[248:251], v[232:235], v[42:45]
	v_mfma_f32_16x16x32_bf16 v[46:49], v[156:159], v[232:235], v[46:49]
	s_waitcnt lgkmcnt(4)
	v_mfma_f32_16x16x32_bf16 v[50:53], v[240:243], v[236:239], v[50:53]
	v_mfma_f32_16x16x32_bf16 v[54:57], v[244:247], v[236:239], v[54:57]
	v_mfma_f32_16x16x32_bf16 v[58:61], v[248:251], v[236:239], v[58:61]
	v_mfma_f32_16x16x32_bf16 v[62:65], v[156:159], v[236:239], v[62:65]
	s_waitcnt lgkmcnt(3)
	v_mfma_f32_16x16x32_bf16 v[74:77], v[160:163], v[224:227], v[74:77]
	s_waitcnt lgkmcnt(2)
	v_mfma_f32_16x16x32_bf16 v[78:81], v[164:167], v[224:227], v[78:81]
	s_waitcnt lgkmcnt(1)
	v_mfma_f32_16x16x32_bf16 v[82:85], v[168:171], v[224:227], v[82:85]
	s_waitcnt lgkmcnt(0)
	v_mfma_f32_16x16x32_bf16 v[86:89], v[122:125], v[224:227], v[86:89]
	v_mfma_f32_16x16x32_bf16 v[90:93], v[160:163], v[228:231], v[90:93]
	v_mfma_f32_16x16x32_bf16 v[94:97], v[164:167], v[228:231], v[94:97]
	v_mfma_f32_16x16x32_bf16 v[98:101], v[168:171], v[228:231], v[98:101]
	v_mfma_f32_16x16x32_bf16 v[102:105], v[122:125], v[228:231], v[102:105]
	v_mfma_f32_16x16x32_bf16 v[106:109], v[160:163], v[232:235], v[106:109]
	v_mfma_f32_16x16x32_bf16 v[110:113], v[164:167], v[232:235], v[110:113]
	v_mfma_f32_16x16x32_bf16 v[114:117], v[168:171], v[232:235], v[114:117]
	v_mfma_f32_16x16x32_bf16 v[118:121], v[122:125], v[232:235], v[118:121]
	v_mfma_f32_16x16x32_bf16 v[208:211], v[160:163], v[236:239], v[208:211]
	v_mfma_f32_16x16x32_bf16 v[212:215], v[164:167], v[236:239], v[212:215]
	v_mfma_f32_16x16x32_bf16 v[216:219], v[168:171], v[236:239], v[216:219]
	v_mfma_f32_16x16x32_bf16 v[220:223], v[122:125], v[236:239], v[220:223]
	s_sub_u32 s46, s46, 1
	s_cmp_lg_u32 s46, 0
	s_cbranch_scc1 .Lffn2_kloop
	s_waitcnt vmcnt(6)
	s_barrier
; #define BLOAD(A_, B_, kt) do { _Pragma("unroll") for (int i = 0; i < 4; ++i) { \
;     A_[i] = *(const u32x4*)((const char*)Ap + (aoff + (unsigned)(32 * i * lda + (kt) * 64) * 2u)); B_[i] = *(const u32x4*)((const char*)Wt + (woff + (unsigned)(32 * i * K + (kt) * 64) * 2u)); } } while (0)
; #define BLOAD(A_, B_, kt) do { _Pragma("unroll") for (int i = 0; i < 4; ++i) { \
;     A_[i] = *(const u32x4*)((const char*)Ap + (aoff + (unsigned)(32 * i * lda + (kt) * 64) * 2u)); B_[i] = *(const u32x4*)((const char*)Wt + (woff + (unsigned)(32 * i * K + (kt) * 64) * 2u)); } } while (0)
; #define BSTORE(A_, B_, buf) do { _Pragma("unroll") for (int i = 0; i < 4; ++i) { \
;     *(u32x4*)&As[(buf) * GBUF + (srow + 32 * i) * LDT + sc8] = A_[i]; \
;     *(u32x4*)&Bs[(buf) * GBUF + (srow + 32 * i) * LDT + sc8] = B_[i]; } } while (0)
; template <int NK>
; DI void gemm_run(PF& pf, const u16* __restrict__ Ap, int lda, const u16* __restrict__ Wt, f32x16 (&acc)[2][2], char* smem) {
;     ...
; #pragma unroll
;   for (int kt = 0; kt < nk; kt += 2) {
;     BCOMP(0);
;     BSTORE(pf.a1, pf.b1, 1);
;     if (kt + 3 < nk) BLOAD(pf.a1, pf.b1, kt + 3);
;     __syncthreads();
;     BCOMP(1);
;     if (kt + 2 < nk) { BSTORE(pf.a0, pf.b0, 0); if (kt + 4 < nk) BLOAD(pf.a0, pf.b0, kt + 4); }
;     __syncthreads();
;   }
	ds_read_b128 v[224:227], v126 offset:0
	ds_read_b128 v[240:243], v128 offset:0
	ds_read_b128 v[244:247], v128 offset:1024
	ds_read_b128 v[248:251], v128 offset:2048
	ds_read_b128 v[156:159], v128 offset:3072
	ds_read_b128 v[228:231], v126 offset:1024
	ds_read_b128 v[232:235], v126 offset:2048
	ds_read_b128 v[236:239], v126 offset:3072
	ds_read_b128 v[160:163], v128 offset:8192
	ds_read_b128 v[164:167], v128 offset:9216
	ds_read_b128 v[168:171], v128 offset:10240
	ds_read_b128 v[122:125], v128 offset:11264
	s_waitcnt lgkmcnt(10)
	v_mfma_f32_16x16x32_bf16 v[2:5], v[240:243], v[224:227], v[2:5]
	s_waitcnt lgkmcnt(9)
	v_mfma_f32_16x16x32_bf16 v[6:9], v[244:247], v[224:227], v[6:9]
	s_waitcnt lgkmcnt(8)
	v_mfma_f32_16x16x32_bf16 v[10:13], v[248:251], v[224:227], v[10:13]
	s_waitcnt lgkmcnt(7)
	v_mfma_f32_16x16x32_bf16 v[14:17], v[156:159], v[224:227], v[14:17]
	s_waitcnt lgkmcnt(6)
	v_mfma_f32_16x16x32_bf16 v[18:21], v[240:243], v[228:231], v[18:21]
	v_mfma_f32_16x16x32_bf16 v[22:25], v[244:247], v[228:231], v[22:25]
	v_mfma_f32_16x16x32_bf16 v[26:29], v[248:251], v[228:231], v[26:29]
	v_mfma_f32_16x16x32_bf16 v[30:33], v[156:159], v[228:231], v[30:33]
	s_waitcnt lgkmcnt(5)
	v_mfma_f32_16x16x32_bf16 v[34:37], v[240:243], v[232:235], v[34:37]
	v_mfma_f32_16x16x32_bf16 v[38:41], v[244:247], v[232:235], v[38:41]
	v_mfma_f32_16x16x32_bf16 v[42:45], v[248:251], v[232:235], v[42:45]
	v_mfma_f32_16x16x32_bf16 v[46:49], v[156:159], v[232:235], v[46:49]
	s_waitcnt lgkmcnt(4)
	v_mfma_f32_16x16x32_bf16 v[50:53], v[240:243], v[236:239], v[50:53]
	v_mfma_f32_16x16x32_bf16 v[54:57], v[244:247], v[236:239], v[54:57]
	v_mfma_f32_16x16x32_bf16 v[58:61], v[248:251], v[236:239], v[58:61]
	v_mfma_f32_16x16x32_bf16 v[62:65], v[156:159], v[236:239], v[62:65]
	s_waitcnt lgkmcnt(3)
	v_mfma_f32_16x16x32_bf16 v[74:77], v[160:163], v[224:227], v[74:77]
	s_waitcnt lgkmcnt(2)
	v_mfma_f32_16x16x32_bf16 v[78:81], v[164:167], v[224:227], v[78:81]
	s_waitcnt lgkmcnt(1)
	v_mfma_f32_16x16x32_bf16 v[82:85], v[168:171], v[224:227], v[82:85]
	s_waitcnt lgkmcnt(0)
	v_mfma_f32_16x16x32_bf16 v[86:89], v[122:125], v[224:227], v[86:89]
	v_mfma_f32_16x16x32_bf16 v[90:93], v[160:163], v[228:231], v[90:93]
	v_mfma_f32_16x16x32_bf16 v[94:97], v[164:167], v[228:231], v[94:97]
	v_mfma_f32_16x16x32_bf16 v[98:101], v[168:171], v[228:231], v[98:101]
	v_mfma_f32_16x16x32_bf16 v[102:105], v[122:125], v[228:231], v[102:105]
	v_mfma_f32_16x16x32_bf16 v[106:109], v[160:163], v[232:235], v[106:109]
	v_mfma_f32_16x16x32_bf16 v[110:113], v[164:167], v[232:235], v[110:113]
	v_mfma_f32_16x16x32_bf16 v[114:117], v[168:171], v[232:235], v[114:117]
	v_mfma_f32_16x16x32_bf16 v[118:121], v[122:125], v[232:235], v[118:121]
	v_mfma_f32_16x16x32_bf16 v[208:211], v[160:163], v[236:239], v[208:211]
	v_mfma_f32_16x16x32_bf16 v[212:215], v[164:167], v[236:239], v[212:215]
	v_mfma_f32_16x16x32_bf16 v[216:219], v[168:171], v[236:239], v[216:219]
	v_mfma_f32_16x16x32_bf16 v[220:223], v[122:125], v[236:239], v[220:223]
	s_waitcnt vmcnt(0)
	s_barrier
	ds_read_b128 v[224:227], v126 offset:24576
	ds_read_b128 v[240:243], v128 offset:24576
	ds_read_b128 v[244:247], v128 offset:25600
	ds_read_b128 v[248:251], v128 offset:26624
	ds_read_b128 v[156:159], v128 offset:27648
	ds_read_b128 v[228:231], v126 offset:25600
	ds_read_b128 v[232:235], v126 offset:26624
	ds_read_b128 v[236:239], v126 offset:27648
	ds_read_b128 v[160:163], v128 offset:32768
	ds_read_b128 v[164:167], v128 offset:33792
	ds_read_b128 v[168:171], v128 offset:34816
	ds_read_b128 v[122:125], v128 offset:35840
	s_waitcnt lgkmcnt(10)
	v_mfma_f32_16x16x32_bf16 v[2:5], v[240:243], v[224:227], v[2:5]
	s_waitcnt lgkmcnt(9)
	v_mfma_f32_16x16x32_bf16 v[6:9], v[244:247], v[224:227], v[6:9]
	s_waitcnt lgkmcnt(8)
	v_mfma_f32_16x16x32_bf16 v[10:13], v[248:251], v[224:227], v[10:13]
	s_waitcnt lgkmcnt(7)
	v_mfma_f32_16x16x32_bf16 v[14:17], v[156:159], v[224:227], v[14:17]
	s_waitcnt lgkmcnt(6)
	v_mfma_f32_16x16x32_bf16 v[18:21], v[240:243], v[228:231], v[18:21]
	v_mfma_f32_16x16x32_bf16 v[22:25], v[244:247], v[228:231], v[22:25]
	v_mfma_f32_16x16x32_bf16 v[26:29], v[248:251], v[228:231], v[26:29]
	v_mfma_f32_16x16x32_bf16 v[30:33], v[156:159], v[228:231], v[30:33]
	s_waitcnt lgkmcnt(5)
	v_mfma_f32_16x16x32_bf16 v[34:37], v[240:243], v[232:235], v[34:37]
	v_mfma_f32_16x16x32_bf16 v[38:41], v[244:247], v[232:235], v[38:41]
	v_mfma_f32_16x16x32_bf16 v[42:45], v[248:251], v[232:235], v[42:45]
	v_mfma_f32_16x16x32_bf16 v[46:49], v[156:159], v[232:235], v[46:49]
	s_waitcnt lgkmcnt(4)
	v_mfma_f32_16x16x32_bf16 v[50:53], v[240:243], v[236:239], v[50:53]
	v_mfma_f32_16x16x32_bf16 v[54:57], v[244:247], v[236:239], v[54:57]
	v_mfma_f32_16x16x32_bf16 v[58:61], v[248:251], v[236:239], v[58:61]
	v_mfma_f32_16x16x32_bf16 v[62:65], v[156:159], v[236:239], v[62:65]
	s_waitcnt lgkmcnt(3)
	v_mfma_f32_16x16x32_bf16 v[74:77], v[160:163], v[224:227], v[74:77]
	s_waitcnt lgkmcnt(2)
	v_mfma_f32_16x16x32_bf16 v[78:81], v[164:167], v[224:227], v[78:81]
	s_waitcnt lgkmcnt(1)
	v_mfma_f32_16x16x32_bf16 v[82:85], v[168:171], v[224:227], v[82:85]
	s_waitcnt lgkmcnt(0)
	v_mfma_f32_16x16x32_bf16 v[86:89], v[122:125], v[224:227], v[86:89]
	v_mfma_f32_16x16x32_bf16 v[90:93], v[160:163], v[228:231], v[90:93]
	v_mfma_f32_16x16x32_bf16 v[94:97], v[164:167], v[228:231], v[94:97]
	v_mfma_f32_16x16x32_bf16 v[98:101], v[168:171], v[228:231], v[98:101]
	v_mfma_f32_16x16x32_bf16 v[102:105], v[122:125], v[228:231], v[102:105]
	v_mfma_f32_16x16x32_bf16 v[106:109], v[160:163], v[232:235], v[106:109]
	v_mfma_f32_16x16x32_bf16 v[110:113], v[164:167], v[232:235], v[110:113]
	v_mfma_f32_16x16x32_bf16 v[114:117], v[168:171], v[232:235], v[114:117]
	v_mfma_f32_16x16x32_bf16 v[118:121], v[122:125], v[232:235], v[118:121]
	v_mfma_f32_16x16x32_bf16 v[208:211], v[160:163], v[236:239], v[208:211]
	v_mfma_f32_16x16x32_bf16 v[212:215], v[164:167], v[236:239], v[212:215]
	v_mfma_f32_16x16x32_bf16 v[216:219], v[168:171], v[236:239], v[216:219]
	v_mfma_f32_16x16x32_bf16 v[220:223], v[122:125], v[236:239], v[220:223]
	s_barrier
	s_mov_b32 s16, 0
